# K-loop LDS-DMA loads in SGPR-base form extended to the residual instance and vcc-based bases (one vector address add left per iteration)
# baseline (speedup 1.0000x reference)
.LBB0_159:
	s_ashr_i32 s29, s28, 31
	s_lshl_b64 s[24:25], s[28:29], 19
	s_add_u32 s24, s34, s24
	s_addc_u32 s25, s35, s25
	s_and_b64 s[30:31], s[18:19], exec
	s_cselect_b32 s29, s25, s41
	s_cselect_b32 s43, s24, s40
	s_ashr_i32 s21, s20, 31
	s_lshl_b64 s[30:31], s[20:21], 19
	s_add_u32 s30, s36, s30
	s_addc_u32 s31, s37, s31
	s_and_b64 s[56:57], s[18:19], exec
	s_cselect_b32 s21, s31, s27
	s_cselect_b32 s55, s30, s26
	s_add_u32 s40, s40, 0x40080
	s_addc_u32 s41, s41, 0
	s_add_u32 s56, s26, 0x100
	s_addc_u32 s57, s27, 0
	s_mov_b32 s58, -2
	s_add_u32 s26, s40, 0xfffc0080
	s_addc_u32 s27, s41, -1
	s_add_i32 s59, 0, 0x10000
	s_cmp_eq_u32 s58, 12
	s_cselect_b32 vcc_hi, s29, s27
	s_cselect_b32 vcc_lo, s43, s26
	v_add_u32_e32 v0, s59, v167
	s_cselect_b32 s27, s21, s57
	s_cselect_b32 s26, s55, s56
	s_add_i32 s62, 0, 0x14000
	ds_read_b128 v[142:145], v0
	ds_read_b128 v[146:149], v0 offset:1024
	ds_read_b128 v[150:153], v0 offset:2048
	ds_read_b128 v[154:157], v0 offset:3072
	v_add_u32_e32 v0, s62, v167
	ds_read_b128 v[158:161], v0
	ds_read_b128 v[162:165], v0 offset:1024
	ds_read_b128 v[174:177], v0 offset:2048
	ds_read_b128 v[178:181], v0 offset:3072
	s_add_i32 m0, s23, 0xc000
	ds_read_b128 v[182:185], v173
	ds_read_b128 v[186:189], v173 offset:1024
	ds_read_b128 v[190:193], v173 offset:2048
	ds_read_b128 v[194:197], v173 offset:3072
	ds_read_b128 v[198:201], v173 offset:4096
	ds_read_b128 v[202:205], v173 offset:5120
	ds_read_b128 v[206:209], v173 offset:6144
	ds_read_b128 v[210:213], v173 offset:7168
	global_load_lds_dwordx4 v138, s[40:41]
	s_add_i32 m0, s23, 0xe000
	s_nop 0
	global_load_lds_dwordx4 v140, s[40:41]
	s_waitcnt vmcnt(8)
	s_waitcnt lgkmcnt(0)
	s_barrier
	s_waitcnt lgkmcnt(0)
	v_mfma_f32_16x16x32_bf16 v[126:129], v[142:145], v[182:185], 0
	v_mfma_f32_16x16x32_bf16 v[126:129], v[146:149], v[186:189], v[126:129]
	v_mfma_f32_16x16x32_bf16 v[122:125], v[154:157], v[186:189], 0
	v_mfma_f32_16x16x32_bf16 v[122:125], v[150:153], v[182:185], v[122:125]
	v_mfma_f32_16x16x32_bf16 v[114:117], v[150:153], v[190:193], 0
	v_mfma_f32_16x16x32_bf16 v[114:117], v[154:157], v[194:197], v[114:117]
	v_mfma_f32_16x16x32_bf16 v[118:121], v[146:149], v[194:197], 0
	v_mfma_f32_16x16x32_bf16 v[118:121], v[142:145], v[190:193], v[118:121]
	v_mfma_f32_16x16x32_bf16 v[110:113], v[142:145], v[198:201], 0
	v_mfma_f32_16x16x32_bf16 v[110:113], v[146:149], v[202:205], v[110:113]
	v_mfma_f32_16x16x32_bf16 v[106:109], v[154:157], v[202:205], 0
	v_mfma_f32_16x16x32_bf16 v[106:109], v[150:153], v[198:201], v[106:109]
	v_mfma_f32_16x16x32_bf16 v[98:101], v[150:153], v[206:209], 0
	v_mfma_f32_16x16x32_bf16 v[98:101], v[154:157], v[210:213], v[98:101]
	v_mfma_f32_16x16x32_bf16 v[102:105], v[146:149], v[210:213], 0
	v_mfma_f32_16x16x32_bf16 v[102:105], v[142:145], v[206:209], v[102:105]
	v_mfma_f32_16x16x32_bf16 v[38:41], v[158:161], v[206:209], 0
	v_mfma_f32_16x16x32_bf16 v[38:41], v[162:165], v[210:213], v[38:41]
	v_mfma_f32_16x16x32_bf16 v[34:37], v[178:181], v[210:213], 0
	v_mfma_f32_16x16x32_bf16 v[34:37], v[174:177], v[206:209], v[34:37]
	v_mfma_f32_16x16x32_bf16 v[46:49], v[174:177], v[198:201], 0
	v_mfma_f32_16x16x32_bf16 v[46:49], v[178:181], v[202:205], v[46:49]
	v_mfma_f32_16x16x32_bf16 v[54:57], v[162:165], v[202:205], 0
	v_mfma_f32_16x16x32_bf16 v[54:57], v[158:161], v[198:201], v[54:57]
	v_mfma_f32_16x16x32_bf16 v[70:73], v[158:161], v[190:193], 0
	v_mfma_f32_16x16x32_bf16 v[70:73], v[162:165], v[194:197], v[70:73]
	v_mfma_f32_16x16x32_bf16 v[62:65], v[178:181], v[194:197], 0
	v_mfma_f32_16x16x32_bf16 v[62:65], v[174:177], v[190:193], v[62:65]
	v_mfma_f32_16x16x32_bf16 v[74:77], v[174:177], v[182:185], 0
	v_mfma_f32_16x16x32_bf16 v[74:77], v[178:181], v[186:189], v[74:77]
	v_mfma_f32_16x16x32_bf16 v[82:85], v[162:165], v[186:189], 0
	v_mfma_f32_16x16x32_bf16 v[82:85], v[158:161], v[182:185], v[82:85]
	s_barrier
	s_add_i32 s59, s59, s44
	s_add_u32 s64, s26, s98
	s_addc_u32 s65, s27, s99
	s_mov_b32 m0, s59
	ds_read_b128 v[182:185], v173 offset:16384
	ds_read_b128 v[186:189], v173 offset:17408
	ds_read_b128 v[190:193], v173 offset:18432
	ds_read_b128 v[194:197], v173 offset:19456
	ds_read_b128 v[198:201], v173 offset:20480
	ds_read_b128 v[202:205], v173 offset:21504
	ds_read_b128 v[206:209], v173 offset:22528
	ds_read_b128 v[210:213], v173 offset:23552
	global_load_lds_dwordx4 v132, s[26:27]
	s_add_i32 m0, s59, 0x2000
	s_add_u32 s60, s26, 0x40000
	s_addc_u32 s61, s27, 0
	s_add_i32 s59, s62, s44
	global_load_lds_dwordx4 v136, s[26:27]
	s_mov_b32 m0, s59
	global_load_lds_dwordx4 v132, s[60:61]
	s_add_i32 m0, s59, 0x2000
	s_nop 0
	global_load_lds_dwordx4 v136, s[60:61]
	s_add_u32 s66, vcc_lo, s98
	s_addc_u32 s67, vcc_hi, s99
	s_mov_b32 m0, s23
	s_nop 0
	global_load_lds_dwordx4 v130, vcc
	s_mov_b32 m0, s45
	s_nop 0
	global_load_lds_dwordx4 v134, vcc
	s_waitcnt vmcnt(8)
	s_waitcnt lgkmcnt(0)
	s_barrier
	s_waitcnt lgkmcnt(0)
	v_mfma_f32_16x16x32_bf16 v[94:97], v[142:145], v[182:185], 0
	v_mfma_f32_16x16x32_bf16 v[94:97], v[146:149], v[186:189], v[94:97]
	v_mfma_f32_16x16x32_bf16 v[90:93], v[154:157], v[186:189], 0
	v_mfma_f32_16x16x32_bf16 v[90:93], v[150:153], v[182:185], v[90:93]
	v_mfma_f32_16x16x32_bf16 v[78:81], v[150:153], v[190:193], 0
	v_mfma_f32_16x16x32_bf16 v[78:81], v[154:157], v[194:197], v[78:81]
	v_mfma_f32_16x16x32_bf16 v[86:89], v[146:149], v[194:197], 0
	v_mfma_f32_16x16x32_bf16 v[86:89], v[142:145], v[190:193], v[86:89]
	v_mfma_f32_16x16x32_bf16 v[66:69], v[142:145], v[198:201], 0
	v_mfma_f32_16x16x32_bf16 v[66:69], v[146:149], v[202:205], v[66:69]
	v_mfma_f32_16x16x32_bf16 v[58:61], v[154:157], v[202:205], 0
	v_mfma_f32_16x16x32_bf16 v[58:61], v[150:153], v[198:201], v[58:61]
	v_mfma_f32_16x16x32_bf16 v[42:45], v[150:153], v[206:209], 0
	v_mfma_f32_16x16x32_bf16 v[42:45], v[154:157], v[210:213], v[42:45]
	v_mfma_f32_16x16x32_bf16 v[50:53], v[146:149], v[210:213], 0
	v_mfma_f32_16x16x32_bf16 v[50:53], v[142:145], v[206:209], v[50:53]
	v_mfma_f32_16x16x32_bf16 v[6:9], v[158:161], v[206:209], 0
	v_mfma_f32_16x16x32_bf16 v[6:9], v[162:165], v[210:213], v[6:9]
	v_mfma_f32_16x16x32_bf16 v[2:5], v[178:181], v[210:213], 0
	v_mfma_f32_16x16x32_bf16 v[2:5], v[174:177], v[206:209], v[2:5]
	v_mfma_f32_16x16x32_bf16 v[10:13], v[174:177], v[198:201], 0
	v_mfma_f32_16x16x32_bf16 v[10:13], v[178:181], v[202:205], v[10:13]
	v_mfma_f32_16x16x32_bf16 v[14:17], v[162:165], v[202:205], 0
	v_mfma_f32_16x16x32_bf16 v[14:17], v[158:161], v[198:201], v[14:17]
	v_mfma_f32_16x16x32_bf16 v[22:25], v[158:161], v[190:193], 0
	v_mfma_f32_16x16x32_bf16 v[22:25], v[162:165], v[194:197], v[22:25]
	v_mfma_f32_16x16x32_bf16 v[18:21], v[178:181], v[194:197], 0
	v_mfma_f32_16x16x32_bf16 v[18:21], v[174:177], v[190:193], v[18:21]
	v_mfma_f32_16x16x32_bf16 v[26:29], v[174:177], v[182:185], 0
	v_mfma_f32_16x16x32_bf16 v[26:29], v[178:181], v[186:189], v[26:29]
	v_mfma_f32_16x16x32_bf16 v[30:33], v[162:165], v[186:189], 0
	v_mfma_f32_16x16x32_bf16 v[30:33], v[158:161], v[182:185], v[30:33]
	s_barrier
	s_add_i32 s59, 0, 0x18000
	v_add_u32_e32 v0, s59, v167
	s_add_i32 s62, 0, 0x1c000
	ds_read_b128 v[142:145], v0
	ds_read_b128 v[146:149], v0 offset:1024
	ds_read_b128 v[150:153], v0 offset:2048
	ds_read_b128 v[154:157], v0 offset:3072
	v_add_u32_e32 v0, s62, v167
	ds_read_b128 v[158:161], v0
	ds_read_b128 v[162:165], v0 offset:1024
	ds_read_b128 v[174:177], v0 offset:2048
	ds_read_b128 v[178:181], v0 offset:3072
	s_add_u32 s60, vcc_lo, 0x40000
	s_addc_u32 s61, vcc_hi, 0
	s_mov_b32 m0, s47
	ds_read_b128 v[182:185], v173 offset:32768
	ds_read_b128 v[186:189], v173 offset:33792
	ds_read_b128 v[190:193], v173 offset:34816
	ds_read_b128 v[194:197], v173 offset:35840
	ds_read_b128 v[198:201], v173 offset:36864
	ds_read_b128 v[202:205], v173 offset:37888
	ds_read_b128 v[206:209], v173 offset:38912
	ds_read_b128 v[210:213], v173 offset:39936
	global_load_lds_dwordx4 v130, s[60:61]
	v_lshl_add_u64 v[222:223], s[60:61], 0, v[134:135]
	s_mov_b32 m0, s49
	s_nop 0
	global_load_lds_dwordx4 v[222:223], off
	s_waitcnt vmcnt(8)
	s_waitcnt lgkmcnt(0)
	s_barrier
	s_waitcnt lgkmcnt(0)
	v_mfma_f32_16x16x32_bf16 v[126:129], v[142:145], v[182:185], v[126:129]
	v_mfma_f32_16x16x32_bf16 v[126:129], v[146:149], v[186:189], v[126:129]
	v_mfma_f32_16x16x32_bf16 v[122:125], v[154:157], v[186:189], v[122:125]
	v_mfma_f32_16x16x32_bf16 v[122:125], v[150:153], v[182:185], v[122:125]
	v_mfma_f32_16x16x32_bf16 v[114:117], v[150:153], v[190:193], v[114:117]
	v_mfma_f32_16x16x32_bf16 v[114:117], v[154:157], v[194:197], v[114:117]
	v_mfma_f32_16x16x32_bf16 v[118:121], v[146:149], v[194:197], v[118:121]
	v_mfma_f32_16x16x32_bf16 v[118:121], v[142:145], v[190:193], v[118:121]
	v_mfma_f32_16x16x32_bf16 v[110:113], v[142:145], v[198:201], v[110:113]
	v_mfma_f32_16x16x32_bf16 v[110:113], v[146:149], v[202:205], v[110:113]
	v_mfma_f32_16x16x32_bf16 v[106:109], v[154:157], v[202:205], v[106:109]
	v_mfma_f32_16x16x32_bf16 v[106:109], v[150:153], v[198:201], v[106:109]
	v_mfma_f32_16x16x32_bf16 v[98:101], v[150:153], v[206:209], v[98:101]
	v_mfma_f32_16x16x32_bf16 v[98:101], v[154:157], v[210:213], v[98:101]
	v_mfma_f32_16x16x32_bf16 v[102:105], v[146:149], v[210:213], v[102:105]
	v_mfma_f32_16x16x32_bf16 v[102:105], v[142:145], v[206:209], v[102:105]
	v_mfma_f32_16x16x32_bf16 v[38:41], v[158:161], v[206:209], v[38:41]
	v_mfma_f32_16x16x32_bf16 v[38:41], v[162:165], v[210:213], v[38:41]
	v_mfma_f32_16x16x32_bf16 v[34:37], v[178:181], v[210:213], v[34:37]
	v_mfma_f32_16x16x32_bf16 v[34:37], v[174:177], v[206:209], v[34:37]
	v_mfma_f32_16x16x32_bf16 v[46:49], v[174:177], v[198:201], v[46:49]
	v_mfma_f32_16x16x32_bf16 v[46:49], v[178:181], v[202:205], v[46:49]
	v_mfma_f32_16x16x32_bf16 v[54:57], v[162:165], v[202:205], v[54:57]
	v_mfma_f32_16x16x32_bf16 v[54:57], v[158:161], v[198:201], v[54:57]
	v_mfma_f32_16x16x32_bf16 v[70:73], v[158:161], v[190:193], v[70:73]
	v_mfma_f32_16x16x32_bf16 v[70:73], v[162:165], v[194:197], v[70:73]
	v_mfma_f32_16x16x32_bf16 v[62:65], v[178:181], v[194:197], v[62:65]
	v_mfma_f32_16x16x32_bf16 v[62:65], v[174:177], v[190:193], v[62:65]
	v_mfma_f32_16x16x32_bf16 v[74:77], v[174:177], v[182:185], v[74:77]
	v_mfma_f32_16x16x32_bf16 v[74:77], v[178:181], v[186:189], v[74:77]
	v_mfma_f32_16x16x32_bf16 v[82:85], v[162:165], v[186:189], v[82:85]
	v_mfma_f32_16x16x32_bf16 v[82:85], v[158:161], v[182:185], v[82:85]
	s_barrier
	s_add_i32 s59, s59, s44
	s_mov_b32 m0, s59
	ds_read_b128 v[182:185], v173 offset:49152
	ds_read_b128 v[186:189], v173 offset:50176
	ds_read_b128 v[190:193], v173 offset:51200
	ds_read_b128 v[194:197], v173 offset:52224
	ds_read_b128 v[198:201], v173 offset:53248
	ds_read_b128 v[202:205], v173 offset:54272
	ds_read_b128 v[206:209], v173 offset:55296
	ds_read_b128 v[210:213], v173 offset:56320
	global_load_lds_dwordx4 v132, s[64:65]
	s_add_i32 m0, s59, 0x2000
	s_add_u32 s26, s26, 0x40080
	s_addc_u32 s27, s27, 0
	s_add_i32 s59, s62, s44
	global_load_lds_dwordx4 v136, s[64:65]
	s_mov_b32 m0, s59
	s_nop 0
	global_load_lds_dwordx4 v132, s[26:27]
	s_add_i32 m0, s59, 0x2000
	s_nop 0
	global_load_lds_dwordx4 v136, s[26:27]
	s_mov_b32 m0, s52
	s_nop 0
	global_load_lds_dwordx4 v130, s[66:67]
	s_mov_b32 m0, s53
	s_nop 0
	global_load_lds_dwordx4 v134, s[66:67]
	s_waitcnt vmcnt(8)
	s_waitcnt lgkmcnt(0)
	s_barrier
	s_waitcnt lgkmcnt(0)
	v_mfma_f32_16x16x32_bf16 v[94:97], v[142:145], v[182:185], v[94:97]
	v_mfma_f32_16x16x32_bf16 v[94:97], v[146:149], v[186:189], v[94:97]
	v_mfma_f32_16x16x32_bf16 v[90:93], v[154:157], v[186:189], v[90:93]
	v_mfma_f32_16x16x32_bf16 v[90:93], v[150:153], v[182:185], v[90:93]
	v_mfma_f32_16x16x32_bf16 v[78:81], v[150:153], v[190:193], v[78:81]
	v_mfma_f32_16x16x32_bf16 v[78:81], v[154:157], v[194:197], v[78:81]
	v_mfma_f32_16x16x32_bf16 v[86:89], v[146:149], v[194:197], v[86:89]
	v_mfma_f32_16x16x32_bf16 v[86:89], v[142:145], v[190:193], v[86:89]
	v_mfma_f32_16x16x32_bf16 v[66:69], v[142:145], v[198:201], v[66:69]
	v_mfma_f32_16x16x32_bf16 v[66:69], v[146:149], v[202:205], v[66:69]
	v_mfma_f32_16x16x32_bf16 v[58:61], v[154:157], v[202:205], v[58:61]
	v_mfma_f32_16x16x32_bf16 v[58:61], v[150:153], v[198:201], v[58:61]
	v_mfma_f32_16x16x32_bf16 v[42:45], v[150:153], v[206:209], v[42:45]
	v_mfma_f32_16x16x32_bf16 v[42:45], v[154:157], v[210:213], v[42:45]
	v_mfma_f32_16x16x32_bf16 v[50:53], v[146:149], v[210:213], v[50:53]
	v_mfma_f32_16x16x32_bf16 v[50:53], v[142:145], v[206:209], v[50:53]
	v_mfma_f32_16x16x32_bf16 v[6:9], v[158:161], v[206:209], v[6:9]
	v_mfma_f32_16x16x32_bf16 v[6:9], v[162:165], v[210:213], v[6:9]
	v_mfma_f32_16x16x32_bf16 v[2:5], v[178:181], v[210:213], v[2:5]
	v_mfma_f32_16x16x32_bf16 v[2:5], v[174:177], v[206:209], v[2:5]
	v_mfma_f32_16x16x32_bf16 v[10:13], v[174:177], v[198:201], v[10:13]
	v_mfma_f32_16x16x32_bf16 v[10:13], v[178:181], v[202:205], v[10:13]
	v_mfma_f32_16x16x32_bf16 v[14:17], v[162:165], v[202:205], v[14:17]
	v_mfma_f32_16x16x32_bf16 v[14:17], v[158:161], v[198:201], v[14:17]
	v_mfma_f32_16x16x32_bf16 v[22:25], v[158:161], v[190:193], v[22:25]
	v_mfma_f32_16x16x32_bf16 v[22:25], v[162:165], v[194:197], v[22:25]
	v_mfma_f32_16x16x32_bf16 v[18:21], v[178:181], v[194:197], v[18:21]
	v_mfma_f32_16x16x32_bf16 v[18:21], v[174:177], v[190:193], v[18:21]
	v_mfma_f32_16x16x32_bf16 v[26:29], v[174:177], v[182:185], v[26:29]
	v_mfma_f32_16x16x32_bf16 v[26:29], v[178:181], v[186:189], v[26:29]
	v_mfma_f32_16x16x32_bf16 v[30:33], v[162:165], v[186:189], v[30:33]
	v_mfma_f32_16x16x32_bf16 v[30:33], v[158:161], v[182:185], v[30:33]
	s_barrier
	s_add_i32 s58, s58, 2
	s_add_u32 s40, s40, 0x100
	s_addc_u32 s41, s41, 0
	s_add_u32 s56, s56, 0x100
	s_addc_u32 s57, s57, 0
	s_cmp_gt_u32 s58, 13
	s_cbranch_scc1 .Lpeel_done_160
.LBB0_160:
	s_add_u32 s26, s40, 0xfffc0080
	s_addc_u32 s27, s41, -1
	s_add_i32 s59, 0, 0x10000
	s_cmp_eq_u32 s58, 12
	s_cselect_b32 vcc_hi, s29, s27
	s_cselect_b32 vcc_lo, s43, s26
	v_add_u32_e32 v0, s59, v167
	s_cselect_b32 s27, s21, s57
	s_cselect_b32 s26, s55, s56
	s_add_i32 s62, 0, 0x14000
	ds_read_b128 v[142:145], v0
	ds_read_b128 v[146:149], v0 offset:1024
	ds_read_b128 v[150:153], v0 offset:2048
	ds_read_b128 v[154:157], v0 offset:3072
	v_add_u32_e32 v0, s62, v167
	ds_read_b128 v[158:161], v0
	ds_read_b128 v[162:165], v0 offset:1024
	ds_read_b128 v[174:177], v0 offset:2048
	ds_read_b128 v[178:181], v0 offset:3072
	s_add_i32 m0, s23, 0xc000
	ds_read_b128 v[182:185], v173
	ds_read_b128 v[186:189], v173 offset:1024
	ds_read_b128 v[190:193], v173 offset:2048
	ds_read_b128 v[194:197], v173 offset:3072
	ds_read_b128 v[198:201], v173 offset:4096
	ds_read_b128 v[202:205], v173 offset:5120
	ds_read_b128 v[206:209], v173 offset:6144
	ds_read_b128 v[210:213], v173 offset:7168
	global_load_lds_dwordx4 v138, s[40:41]
	s_add_i32 m0, s23, 0xe000
	s_nop 0
	global_load_lds_dwordx4 v140, s[40:41]
	s_waitcnt vmcnt(8)
	s_waitcnt lgkmcnt(0)
	s_barrier
	s_waitcnt lgkmcnt(0)
	v_mfma_f32_16x16x32_bf16 v[126:129], v[142:145], v[182:185], v[126:129]
	v_mfma_f32_16x16x32_bf16 v[126:129], v[146:149], v[186:189], v[126:129]
	v_mfma_f32_16x16x32_bf16 v[122:125], v[154:157], v[186:189], v[122:125]
	v_mfma_f32_16x16x32_bf16 v[122:125], v[150:153], v[182:185], v[122:125]
	v_mfma_f32_16x16x32_bf16 v[114:117], v[150:153], v[190:193], v[114:117]
	v_mfma_f32_16x16x32_bf16 v[114:117], v[154:157], v[194:197], v[114:117]
	v_mfma_f32_16x16x32_bf16 v[118:121], v[146:149], v[194:197], v[118:121]
	v_mfma_f32_16x16x32_bf16 v[118:121], v[142:145], v[190:193], v[118:121]
	v_mfma_f32_16x16x32_bf16 v[110:113], v[142:145], v[198:201], v[110:113]
	v_mfma_f32_16x16x32_bf16 v[110:113], v[146:149], v[202:205], v[110:113]
	v_mfma_f32_16x16x32_bf16 v[106:109], v[154:157], v[202:205], v[106:109]
	v_mfma_f32_16x16x32_bf16 v[106:109], v[150:153], v[198:201], v[106:109]
	v_mfma_f32_16x16x32_bf16 v[98:101], v[150:153], v[206:209], v[98:101]
	v_mfma_f32_16x16x32_bf16 v[98:101], v[154:157], v[210:213], v[98:101]
	v_mfma_f32_16x16x32_bf16 v[102:105], v[146:149], v[210:213], v[102:105]
	v_mfma_f32_16x16x32_bf16 v[102:105], v[142:145], v[206:209], v[102:105]
	v_mfma_f32_16x16x32_bf16 v[38:41], v[158:161], v[206:209], v[38:41]
	v_mfma_f32_16x16x32_bf16 v[38:41], v[162:165], v[210:213], v[38:41]
	v_mfma_f32_16x16x32_bf16 v[34:37], v[178:181], v[210:213], v[34:37]
	v_mfma_f32_16x16x32_bf16 v[34:37], v[174:177], v[206:209], v[34:37]
	v_mfma_f32_16x16x32_bf16 v[46:49], v[174:177], v[198:201], v[46:49]
	v_mfma_f32_16x16x32_bf16 v[46:49], v[178:181], v[202:205], v[46:49]
	v_mfma_f32_16x16x32_bf16 v[54:57], v[162:165], v[202:205], v[54:57]
	v_mfma_f32_16x16x32_bf16 v[54:57], v[158:161], v[198:201], v[54:57]
	v_mfma_f32_16x16x32_bf16 v[70:73], v[158:161], v[190:193], v[70:73]
	v_mfma_f32_16x16x32_bf16 v[70:73], v[162:165], v[194:197], v[70:73]
	v_mfma_f32_16x16x32_bf16 v[62:65], v[178:181], v[194:197], v[62:65]
	v_mfma_f32_16x16x32_bf16 v[62:65], v[174:177], v[190:193], v[62:65]
	v_mfma_f32_16x16x32_bf16 v[74:77], v[174:177], v[182:185], v[74:77]
	v_mfma_f32_16x16x32_bf16 v[74:77], v[178:181], v[186:189], v[74:77]
	v_mfma_f32_16x16x32_bf16 v[82:85], v[162:165], v[186:189], v[82:85]
	v_mfma_f32_16x16x32_bf16 v[82:85], v[158:161], v[182:185], v[82:85]
	s_barrier
	s_add_i32 s59, s59, s44
	s_add_u32 s64, s26, s98
	s_addc_u32 s65, s27, s99
	s_mov_b32 m0, s59
	ds_read_b128 v[182:185], v173 offset:16384
	ds_read_b128 v[186:189], v173 offset:17408
	ds_read_b128 v[190:193], v173 offset:18432
	ds_read_b128 v[194:197], v173 offset:19456
	ds_read_b128 v[198:201], v173 offset:20480
	ds_read_b128 v[202:205], v173 offset:21504
	ds_read_b128 v[206:209], v173 offset:22528
	ds_read_b128 v[210:213], v173 offset:23552
	global_load_lds_dwordx4 v132, s[26:27]
	s_add_i32 m0, s59, 0x2000
	s_add_u32 s60, s26, 0x40000
	s_addc_u32 s61, s27, 0
	s_add_i32 s59, s62, s44
	global_load_lds_dwordx4 v136, s[26:27]
	s_mov_b32 m0, s59
	global_load_lds_dwordx4 v132, s[60:61]
	s_add_i32 m0, s59, 0x2000
	s_nop 0
	global_load_lds_dwordx4 v136, s[60:61]
	s_add_u32 s66, vcc_lo, s98
	s_addc_u32 s67, vcc_hi, s99
	s_mov_b32 m0, s23
	s_nop 0
	global_load_lds_dwordx4 v130, vcc
	s_mov_b32 m0, s45
	s_nop 0
	global_load_lds_dwordx4 v134, vcc
	s_waitcnt vmcnt(8)
	s_waitcnt lgkmcnt(0)
	s_barrier
	s_waitcnt lgkmcnt(0)
	v_mfma_f32_16x16x32_bf16 v[94:97], v[142:145], v[182:185], v[94:97]
	v_mfma_f32_16x16x32_bf16 v[94:97], v[146:149], v[186:189], v[94:97]
	v_mfma_f32_16x16x32_bf16 v[90:93], v[154:157], v[186:189], v[90:93]
	v_mfma_f32_16x16x32_bf16 v[90:93], v[150:153], v[182:185], v[90:93]
	v_mfma_f32_16x16x32_bf16 v[78:81], v[150:153], v[190:193], v[78:81]
	v_mfma_f32_16x16x32_bf16 v[78:81], v[154:157], v[194:197], v[78:81]
	v_mfma_f32_16x16x32_bf16 v[86:89], v[146:149], v[194:197], v[86:89]
	v_mfma_f32_16x16x32_bf16 v[86:89], v[142:145], v[190:193], v[86:89]
	v_mfma_f32_16x16x32_bf16 v[66:69], v[142:145], v[198:201], v[66:69]
	v_mfma_f32_16x16x32_bf16 v[66:69], v[146:149], v[202:205], v[66:69]
	v_mfma_f32_16x16x32_bf16 v[58:61], v[154:157], v[202:205], v[58:61]
	v_mfma_f32_16x16x32_bf16 v[58:61], v[150:153], v[198:201], v[58:61]
	v_mfma_f32_16x16x32_bf16 v[42:45], v[150:153], v[206:209], v[42:45]
	v_mfma_f32_16x16x32_bf16 v[42:45], v[154:157], v[210:213], v[42:45]
	v_mfma_f32_16x16x32_bf16 v[50:53], v[146:149], v[210:213], v[50:53]
	v_mfma_f32_16x16x32_bf16 v[50:53], v[142:145], v[206:209], v[50:53]
	v_mfma_f32_16x16x32_bf16 v[6:9], v[158:161], v[206:209], v[6:9]
	v_mfma_f32_16x16x32_bf16 v[6:9], v[162:165], v[210:213], v[6:9]
	v_mfma_f32_16x16x32_bf16 v[2:5], v[178:181], v[210:213], v[2:5]
	v_mfma_f32_16x16x32_bf16 v[2:5], v[174:177], v[206:209], v[2:5]
	v_mfma_f32_16x16x32_bf16 v[10:13], v[174:177], v[198:201], v[10:13]
	v_mfma_f32_16x16x32_bf16 v[10:13], v[178:181], v[202:205], v[10:13]
	v_mfma_f32_16x16x32_bf16 v[14:17], v[162:165], v[202:205], v[14:17]
	v_mfma_f32_16x16x32_bf16 v[14:17], v[158:161], v[198:201], v[14:17]
	v_mfma_f32_16x16x32_bf16 v[22:25], v[158:161], v[190:193], v[22:25]
	v_mfma_f32_16x16x32_bf16 v[22:25], v[162:165], v[194:197], v[22:25]
	v_mfma_f32_16x16x32_bf16 v[18:21], v[178:181], v[194:197], v[18:21]
	v_mfma_f32_16x16x32_bf16 v[18:21], v[174:177], v[190:193], v[18:21]
	v_mfma_f32_16x16x32_bf16 v[26:29], v[174:177], v[182:185], v[26:29]
	v_mfma_f32_16x16x32_bf16 v[26:29], v[178:181], v[186:189], v[26:29]
	v_mfma_f32_16x16x32_bf16 v[30:33], v[162:165], v[186:189], v[30:33]
	v_mfma_f32_16x16x32_bf16 v[30:33], v[158:161], v[182:185], v[30:33]
	s_barrier
	s_add_i32 s59, 0, 0x18000
	v_add_u32_e32 v0, s59, v167
	s_add_i32 s62, 0, 0x1c000
	ds_read_b128 v[142:145], v0
	ds_read_b128 v[146:149], v0 offset:1024
	ds_read_b128 v[150:153], v0 offset:2048
	ds_read_b128 v[154:157], v0 offset:3072
	v_add_u32_e32 v0, s62, v167
	ds_read_b128 v[158:161], v0
	ds_read_b128 v[162:165], v0 offset:1024
	ds_read_b128 v[174:177], v0 offset:2048
	ds_read_b128 v[178:181], v0 offset:3072
	s_add_u32 s60, vcc_lo, 0x40000
	s_addc_u32 s61, vcc_hi, 0
	s_mov_b32 m0, s47
	ds_read_b128 v[182:185], v173 offset:32768
	ds_read_b128 v[186:189], v173 offset:33792
	ds_read_b128 v[190:193], v173 offset:34816
	ds_read_b128 v[194:197], v173 offset:35840
	ds_read_b128 v[198:201], v173 offset:36864
	ds_read_b128 v[202:205], v173 offset:37888
	ds_read_b128 v[206:209], v173 offset:38912
	ds_read_b128 v[210:213], v173 offset:39936
	global_load_lds_dwordx4 v130, s[60:61]
	s_mov_b32 m0, s49
	s_nop 0
	global_load_lds_dwordx4 v134, s[60:61]
	s_waitcnt vmcnt(8)
	s_waitcnt lgkmcnt(0)
	s_barrier
	s_waitcnt lgkmcnt(0)
	v_mfma_f32_16x16x32_bf16 v[126:129], v[142:145], v[182:185], v[126:129]
	v_mfma_f32_16x16x32_bf16 v[126:129], v[146:149], v[186:189], v[126:129]
	v_mfma_f32_16x16x32_bf16 v[122:125], v[154:157], v[186:189], v[122:125]
	v_mfma_f32_16x16x32_bf16 v[122:125], v[150:153], v[182:185], v[122:125]
	v_mfma_f32_16x16x32_bf16 v[114:117], v[150:153], v[190:193], v[114:117]
	v_mfma_f32_16x16x32_bf16 v[114:117], v[154:157], v[194:197], v[114:117]
	v_mfma_f32_16x16x32_bf16 v[118:121], v[146:149], v[194:197], v[118:121]
	v_mfma_f32_16x16x32_bf16 v[118:121], v[142:145], v[190:193], v[118:121]
	v_mfma_f32_16x16x32_bf16 v[110:113], v[142:145], v[198:201], v[110:113]
	v_mfma_f32_16x16x32_bf16 v[110:113], v[146:149], v[202:205], v[110:113]
	v_mfma_f32_16x16x32_bf16 v[106:109], v[154:157], v[202:205], v[106:109]
	v_mfma_f32_16x16x32_bf16 v[106:109], v[150:153], v[198:201], v[106:109]
	v_mfma_f32_16x16x32_bf16 v[98:101], v[150:153], v[206:209], v[98:101]
	v_mfma_f32_16x16x32_bf16 v[98:101], v[154:157], v[210:213], v[98:101]
	v_mfma_f32_16x16x32_bf16 v[102:105], v[146:149], v[210:213], v[102:105]
	v_mfma_f32_16x16x32_bf16 v[102:105], v[142:145], v[206:209], v[102:105]
	v_mfma_f32_16x16x32_bf16 v[38:41], v[158:161], v[206:209], v[38:41]
	v_mfma_f32_16x16x32_bf16 v[38:41], v[162:165], v[210:213], v[38:41]
	v_mfma_f32_16x16x32_bf16 v[34:37], v[178:181], v[210:213], v[34:37]
	v_mfma_f32_16x16x32_bf16 v[34:37], v[174:177], v[206:209], v[34:37]
	v_mfma_f32_16x16x32_bf16 v[46:49], v[174:177], v[198:201], v[46:49]
	v_mfma_f32_16x16x32_bf16 v[46:49], v[178:181], v[202:205], v[46:49]
	v_mfma_f32_16x16x32_bf16 v[54:57], v[162:165], v[202:205], v[54:57]
	v_mfma_f32_16x16x32_bf16 v[54:57], v[158:161], v[198:201], v[54:57]
	v_mfma_f32_16x16x32_bf16 v[70:73], v[158:161], v[190:193], v[70:73]
	v_mfma_f32_16x16x32_bf16 v[70:73], v[162:165], v[194:197], v[70:73]
	v_mfma_f32_16x16x32_bf16 v[62:65], v[178:181], v[194:197], v[62:65]
	v_mfma_f32_16x16x32_bf16 v[62:65], v[174:177], v[190:193], v[62:65]
	v_mfma_f32_16x16x32_bf16 v[74:77], v[174:177], v[182:185], v[74:77]
	v_mfma_f32_16x16x32_bf16 v[74:77], v[178:181], v[186:189], v[74:77]
	v_mfma_f32_16x16x32_bf16 v[82:85], v[162:165], v[186:189], v[82:85]
	v_mfma_f32_16x16x32_bf16 v[82:85], v[158:161], v[182:185], v[82:85]
	s_barrier
	s_add_i32 s59, s59, s44
	s_mov_b32 m0, s59
	ds_read_b128 v[182:185], v173 offset:49152
	ds_read_b128 v[186:189], v173 offset:50176
	ds_read_b128 v[190:193], v173 offset:51200
	ds_read_b128 v[194:197], v173 offset:52224
	ds_read_b128 v[198:201], v173 offset:53248
	ds_read_b128 v[202:205], v173 offset:54272
	ds_read_b128 v[206:209], v173 offset:55296
	ds_read_b128 v[210:213], v173 offset:56320
	global_load_lds_dwordx4 v132, s[64:65]
	s_add_i32 m0, s59, 0x2000
	s_add_u32 s26, s26, 0x40080
	s_addc_u32 s27, s27, 0
	s_add_i32 s59, s62, s44
	global_load_lds_dwordx4 v136, s[64:65]
	s_mov_b32 m0, s59
	s_nop 0
	global_load_lds_dwordx4 v132, s[26:27]
	s_add_i32 m0, s59, 0x2000
	s_nop 0
	global_load_lds_dwordx4 v136, s[26:27]
	s_mov_b32 m0, s52
	s_nop 0
	global_load_lds_dwordx4 v130, s[66:67]
	s_mov_b32 m0, s53
	s_nop 0
	global_load_lds_dwordx4 v134, s[66:67]
	s_waitcnt vmcnt(8)
	s_waitcnt lgkmcnt(0)
	s_barrier
	s_waitcnt lgkmcnt(0)
	v_mfma_f32_16x16x32_bf16 v[94:97], v[142:145], v[182:185], v[94:97]
	v_mfma_f32_16x16x32_bf16 v[94:97], v[146:149], v[186:189], v[94:97]
	v_mfma_f32_16x16x32_bf16 v[90:93], v[154:157], v[186:189], v[90:93]
	v_mfma_f32_16x16x32_bf16 v[90:93], v[150:153], v[182:185], v[90:93]
	v_mfma_f32_16x16x32_bf16 v[78:81], v[150:153], v[190:193], v[78:81]
	v_mfma_f32_16x16x32_bf16 v[78:81], v[154:157], v[194:197], v[78:81]
	v_mfma_f32_16x16x32_bf16 v[86:89], v[146:149], v[194:197], v[86:89]
	v_mfma_f32_16x16x32_bf16 v[86:89], v[142:145], v[190:193], v[86:89]
	v_mfma_f32_16x16x32_bf16 v[66:69], v[142:145], v[198:201], v[66:69]
	v_mfma_f32_16x16x32_bf16 v[66:69], v[146:149], v[202:205], v[66:69]
	v_mfma_f32_16x16x32_bf16 v[58:61], v[154:157], v[202:205], v[58:61]
	v_mfma_f32_16x16x32_bf16 v[58:61], v[150:153], v[198:201], v[58:61]
	v_mfma_f32_16x16x32_bf16 v[42:45], v[150:153], v[206:209], v[42:45]
	v_mfma_f32_16x16x32_bf16 v[42:45], v[154:157], v[210:213], v[42:45]
	v_mfma_f32_16x16x32_bf16 v[50:53], v[146:149], v[210:213], v[50:53]
	v_mfma_f32_16x16x32_bf16 v[50:53], v[142:145], v[206:209], v[50:53]
	v_mfma_f32_16x16x32_bf16 v[6:9], v[158:161], v[206:209], v[6:9]
	v_mfma_f32_16x16x32_bf16 v[6:9], v[162:165], v[210:213], v[6:9]
	v_mfma_f32_16x16x32_bf16 v[2:5], v[178:181], v[210:213], v[2:5]
	v_mfma_f32_16x16x32_bf16 v[2:5], v[174:177], v[206:209], v[2:5]
	v_mfma_f32_16x16x32_bf16 v[10:13], v[174:177], v[198:201], v[10:13]
	v_mfma_f32_16x16x32_bf16 v[10:13], v[178:181], v[202:205], v[10:13]
	v_mfma_f32_16x16x32_bf16 v[14:17], v[162:165], v[202:205], v[14:17]
	v_mfma_f32_16x16x32_bf16 v[14:17], v[158:161], v[198:201], v[14:17]
	v_mfma_f32_16x16x32_bf16 v[22:25], v[158:161], v[190:193], v[22:25]
	v_mfma_f32_16x16x32_bf16 v[22:25], v[162:165], v[194:197], v[22:25]
	v_mfma_f32_16x16x32_bf16 v[18:21], v[178:181], v[194:197], v[18:21]
	v_mfma_f32_16x16x32_bf16 v[18:21], v[174:177], v[190:193], v[18:21]
	v_mfma_f32_16x16x32_bf16 v[26:29], v[174:177], v[182:185], v[26:29]
	v_mfma_f32_16x16x32_bf16 v[26:29], v[178:181], v[186:189], v[26:29]
	v_mfma_f32_16x16x32_bf16 v[30:33], v[162:165], v[186:189], v[30:33]
	v_mfma_f32_16x16x32_bf16 v[30:33], v[158:161], v[182:185], v[30:33]
	s_barrier
	s_add_i32 s58, s58, 2
	s_add_u32 s40, s40, 0x100
	s_addc_u32 s41, s41, 0
	s_add_u32 s56, s56, 0x100
	s_addc_u32 s57, s57, 0
	s_cmp_gt_u32 s58, 13
	s_cbranch_scc0 .LBB0_160

.LBB0_216:
	s_add_i32 s13, s61, -2
	s_add_u32 s28, s28, 0x80
	s_addc_u32 s29, s29, 0
	s_add_u32 s23, s40, 0x100
	s_addc_u32 s40, s41, 0
	s_mov_b32 s30, 0
	s_add_i32 s41, s30, 2
	s_add_u32 vcc_lo, s28, 0x80
	s_addc_u32 s31, s29, 0
	s_add_i32 s62, 0, 0x10000
	s_cmp_eq_u32 s13, s30
	s_cselect_b32 s31, s25, s31
	s_cselect_b32 s30, s24, vcc_lo
	v_add_u32_e32 v145, s62, v175
	s_cselect_b32 vcc_hi, s27, s40
	s_cselect_b32 vcc_lo, s26, s23
	s_add_i32 s63, 0, 0x14000
	ds_read_b128 v[130:133], v145
	ds_read_b128 v[134:137], v145 offset:1024
	ds_read_b128 v[152:155], v145 offset:2048
	ds_read_b128 v[156:159], v145 offset:3072
	v_add_u32_e32 v145, s63, v175
	ds_read_b128 v[160:163], v145
	ds_read_b128 v[164:167], v145 offset:1024
	ds_read_b128 v[168:171], v145 offset:2048
	ds_read_b128 v[186:189], v145 offset:3072
	s_add_i32 m0, s93, 0xc000
	ds_read_b128 v[190:193], v184
	ds_read_b128 v[194:197], v184 offset:1024
	ds_read_b128 v[198:201], v184 offset:2048
	ds_read_b128 v[202:205], v184 offset:3072
	ds_read_b128 v[206:209], v184 offset:4096
	ds_read_b128 v[210:213], v184 offset:5120
	ds_read_b128 v[214:217], v184 offset:6144
	ds_read_b128 v[218:221], v184 offset:7168
	global_load_lds_dwordx4 v148, s[28:29]
	s_add_i32 m0, s93, 0xe000
	s_nop 0
	global_load_lds_dwordx4 v150, s[28:29]
	s_waitcnt vmcnt(8)
	s_waitcnt lgkmcnt(0)
	s_barrier
	s_waitcnt lgkmcnt(0)
	v_mfma_f32_16x16x32_bf16 v[126:129], v[130:133], v[190:193], 0
	v_mfma_f32_16x16x32_bf16 v[126:129], v[134:137], v[194:197], v[126:129]
	v_mfma_f32_16x16x32_bf16 v[122:125], v[156:159], v[194:197], 0
	v_mfma_f32_16x16x32_bf16 v[122:125], v[152:155], v[190:193], v[122:125]
	v_mfma_f32_16x16x32_bf16 v[106:109], v[152:155], v[198:201], 0
	v_mfma_f32_16x16x32_bf16 v[106:109], v[156:159], v[202:205], v[106:109]
	v_mfma_f32_16x16x32_bf16 v[110:113], v[134:137], v[202:205], 0
	v_mfma_f32_16x16x32_bf16 v[110:113], v[130:133], v[198:201], v[110:113]
	v_mfma_f32_16x16x32_bf16 v[94:97], v[130:133], v[206:209], 0
	v_mfma_f32_16x16x32_bf16 v[94:97], v[134:137], v[210:213], v[94:97]
	v_mfma_f32_16x16x32_bf16 v[90:93], v[156:159], v[210:213], 0
	v_mfma_f32_16x16x32_bf16 v[90:93], v[152:155], v[206:209], v[90:93]
	v_mfma_f32_16x16x32_bf16 v[74:77], v[152:155], v[214:217], 0
	v_mfma_f32_16x16x32_bf16 v[74:77], v[156:159], v[218:221], v[74:77]
	v_mfma_f32_16x16x32_bf16 v[78:81], v[134:137], v[218:221], 0
	v_mfma_f32_16x16x32_bf16 v[78:81], v[130:133], v[214:217], v[78:81]
	v_mfma_f32_16x16x32_bf16 v[70:73], v[160:163], v[214:217], 0
	v_mfma_f32_16x16x32_bf16 v[70:73], v[164:167], v[218:221], v[70:73]
	v_mfma_f32_16x16x32_bf16 v[66:69], v[186:189], v[218:221], 0
	v_mfma_f32_16x16x32_bf16 v[66:69], v[168:171], v[214:217], v[66:69]
	v_mfma_f32_16x16x32_bf16 v[82:85], v[168:171], v[206:209], 0
	v_mfma_f32_16x16x32_bf16 v[82:85], v[186:189], v[210:213], v[82:85]
	v_mfma_f32_16x16x32_bf16 v[86:89], v[164:167], v[210:213], 0
	v_mfma_f32_16x16x32_bf16 v[86:89], v[160:163], v[206:209], v[86:89]
	v_mfma_f32_16x16x32_bf16 v[102:105], v[160:163], v[198:201], 0
	v_mfma_f32_16x16x32_bf16 v[102:105], v[164:167], v[202:205], v[102:105]
	v_mfma_f32_16x16x32_bf16 v[98:101], v[186:189], v[202:205], 0
	v_mfma_f32_16x16x32_bf16 v[98:101], v[168:171], v[198:201], v[98:101]
	v_mfma_f32_16x16x32_bf16 v[114:117], v[168:171], v[190:193], 0
	v_mfma_f32_16x16x32_bf16 v[114:117], v[186:189], v[194:197], v[114:117]
	v_mfma_f32_16x16x32_bf16 v[118:121], v[164:167], v[194:197], 0
	v_mfma_f32_16x16x32_bf16 v[118:121], v[160:163], v[190:193], v[118:121]
	s_barrier
	s_add_i32 s62, s62, s49
	s_add_u32 s64, vcc_lo, s98
	s_addc_u32 s65, vcc_hi, s99
	s_mov_b32 m0, s62
	ds_read_b128 v[190:193], v184 offset:16384
	ds_read_b128 v[194:197], v184 offset:17408
	ds_read_b128 v[198:201], v184 offset:18432
	ds_read_b128 v[202:205], v184 offset:19456
	ds_read_b128 v[206:209], v184 offset:20480
	ds_read_b128 v[210:213], v184 offset:21504
	ds_read_b128 v[214:217], v184 offset:22528
	ds_read_b128 v[218:221], v184 offset:23552
	global_load_lds_dwordx4 v0, vcc
	s_add_i32 m0, s62, 0x2000
	v_lshl_add_u64 v[222:223], vcc, 0, v[142:143]
	s_add_u32 vcc_lo, vcc_lo, s96
	s_addc_u32 vcc_hi, vcc_hi, 0
	s_add_i32 s62, s63, s49
	global_load_lds_dwordx4 v[222:223], off
	s_add_u32 s66, vcc_lo, s98
	s_addc_u32 s67, vcc_hi, s99
	s_mov_b32 m0, s62
	global_load_lds_dwordx4 v0, vcc
	s_add_i32 m0, s62, 0x2000
	s_add_u32 s68, s30, s98
	s_addc_u32 s69, s31, s99
	global_load_lds_dwordx4 v142, vcc
	s_mov_b32 m0, s93
	global_load_lds_dwordx4 v138, s[30:31]
	s_mov_b32 m0, s88
	s_nop 0
	global_load_lds_dwordx4 v140, s[30:31]
	s_waitcnt vmcnt(8)
	s_waitcnt lgkmcnt(0)
	s_barrier
	s_waitcnt lgkmcnt(0)
	v_mfma_f32_16x16x32_bf16 v[62:65], v[130:133], v[190:193], 0
	v_mfma_f32_16x16x32_bf16 v[62:65], v[134:137], v[194:197], v[62:65]
	v_mfma_f32_16x16x32_bf16 v[58:61], v[156:159], v[194:197], 0
	v_mfma_f32_16x16x32_bf16 v[58:61], v[152:155], v[190:193], v[58:61]
	v_mfma_f32_16x16x32_bf16 v[42:45], v[152:155], v[198:201], 0
	v_mfma_f32_16x16x32_bf16 v[42:45], v[156:159], v[202:205], v[42:45]
	v_mfma_f32_16x16x32_bf16 v[46:49], v[134:137], v[202:205], 0
	v_mfma_f32_16x16x32_bf16 v[46:49], v[130:133], v[198:201], v[46:49]
	v_mfma_f32_16x16x32_bf16 v[30:33], v[130:133], v[206:209], 0
	v_mfma_f32_16x16x32_bf16 v[30:33], v[134:137], v[210:213], v[30:33]
	v_mfma_f32_16x16x32_bf16 v[26:29], v[156:159], v[210:213], 0
	v_mfma_f32_16x16x32_bf16 v[26:29], v[152:155], v[206:209], v[26:29]
	v_mfma_f32_16x16x32_bf16 v[10:13], v[152:155], v[214:217], 0
	v_mfma_f32_16x16x32_bf16 v[10:13], v[156:159], v[218:221], v[10:13]
	v_mfma_f32_16x16x32_bf16 v[14:17], v[134:137], v[218:221], 0
	v_mfma_f32_16x16x32_bf16 v[14:17], v[130:133], v[214:217], v[14:17]
	v_mfma_f32_16x16x32_bf16 v[6:9], v[160:163], v[214:217], 0
	v_mfma_f32_16x16x32_bf16 v[6:9], v[164:167], v[218:221], v[6:9]
	v_mfma_f32_16x16x32_bf16 v[2:5], v[186:189], v[218:221], 0
	v_mfma_f32_16x16x32_bf16 v[2:5], v[168:171], v[214:217], v[2:5]
	v_mfma_f32_16x16x32_bf16 v[18:21], v[168:171], v[206:209], 0
	v_mfma_f32_16x16x32_bf16 v[18:21], v[186:189], v[210:213], v[18:21]
	v_mfma_f32_16x16x32_bf16 v[22:25], v[164:167], v[210:213], 0
	v_mfma_f32_16x16x32_bf16 v[22:25], v[160:163], v[206:209], v[22:25]
	v_mfma_f32_16x16x32_bf16 v[38:41], v[160:163], v[198:201], 0
	v_mfma_f32_16x16x32_bf16 v[38:41], v[164:167], v[202:205], v[38:41]
	v_mfma_f32_16x16x32_bf16 v[34:37], v[186:189], v[202:205], 0
	v_mfma_f32_16x16x32_bf16 v[34:37], v[168:171], v[198:201], v[34:37]
	v_mfma_f32_16x16x32_bf16 v[50:53], v[168:171], v[190:193], 0
	v_mfma_f32_16x16x32_bf16 v[50:53], v[186:189], v[194:197], v[50:53]
	v_mfma_f32_16x16x32_bf16 v[54:57], v[164:167], v[194:197], 0
	v_mfma_f32_16x16x32_bf16 v[54:57], v[160:163], v[190:193], v[54:57]
	s_barrier
	s_add_i32 s62, 0, 0x18000
	v_add_u32_e32 v145, s62, v175
	s_add_i32 s63, 0, 0x1c000
	ds_read_b128 v[130:133], v145
	ds_read_b128 v[134:137], v145 offset:1024
	ds_read_b128 v[152:155], v145 offset:2048
	ds_read_b128 v[156:159], v145 offset:3072
	v_add_u32_e32 v145, s63, v175
	ds_read_b128 v[160:163], v145
	ds_read_b128 v[164:167], v145 offset:1024
	ds_read_b128 v[168:171], v145 offset:2048
	ds_read_b128 v[186:189], v145 offset:3072
	s_add_u32 s30, s30, s96
	s_addc_u32 s31, s31, 0
	s_mov_b32 m0, s89
	ds_read_b128 v[190:193], v184 offset:32768
	ds_read_b128 v[194:197], v184 offset:33792
	ds_read_b128 v[198:201], v184 offset:34816
	ds_read_b128 v[202:205], v184 offset:35840
	ds_read_b128 v[206:209], v184 offset:36864
	ds_read_b128 v[210:213], v184 offset:37888
	ds_read_b128 v[214:217], v184 offset:38912
	ds_read_b128 v[218:221], v184 offset:39936
	global_load_lds_dwordx4 v138, s[30:31]
	v_lshl_add_u64 v[244:245], s[30:31], 0, v[140:141]
	s_mov_b32 m0, s52
	s_nop 0
	global_load_lds_dwordx4 v[244:245], off
	s_waitcnt vmcnt(8)
	s_waitcnt lgkmcnt(0)
	s_barrier
	s_waitcnt lgkmcnt(0)
	v_mfma_f32_16x16x32_bf16 v[126:129], v[130:133], v[190:193], v[126:129]
	v_mfma_f32_16x16x32_bf16 v[126:129], v[134:137], v[194:197], v[126:129]
	v_mfma_f32_16x16x32_bf16 v[122:125], v[156:159], v[194:197], v[122:125]
	v_mfma_f32_16x16x32_bf16 v[122:125], v[152:155], v[190:193], v[122:125]
	v_mfma_f32_16x16x32_bf16 v[106:109], v[152:155], v[198:201], v[106:109]
	v_mfma_f32_16x16x32_bf16 v[106:109], v[156:159], v[202:205], v[106:109]
	v_mfma_f32_16x16x32_bf16 v[110:113], v[134:137], v[202:205], v[110:113]
	v_mfma_f32_16x16x32_bf16 v[110:113], v[130:133], v[198:201], v[110:113]
	v_mfma_f32_16x16x32_bf16 v[94:97], v[130:133], v[206:209], v[94:97]
	v_mfma_f32_16x16x32_bf16 v[94:97], v[134:137], v[210:213], v[94:97]
	v_mfma_f32_16x16x32_bf16 v[90:93], v[156:159], v[210:213], v[90:93]
	v_mfma_f32_16x16x32_bf16 v[90:93], v[152:155], v[206:209], v[90:93]
	v_mfma_f32_16x16x32_bf16 v[74:77], v[152:155], v[214:217], v[74:77]
	v_mfma_f32_16x16x32_bf16 v[74:77], v[156:159], v[218:221], v[74:77]
	v_mfma_f32_16x16x32_bf16 v[78:81], v[134:137], v[218:221], v[78:81]
	v_mfma_f32_16x16x32_bf16 v[78:81], v[130:133], v[214:217], v[78:81]
	v_mfma_f32_16x16x32_bf16 v[70:73], v[160:163], v[214:217], v[70:73]
	v_mfma_f32_16x16x32_bf16 v[70:73], v[164:167], v[218:221], v[70:73]
	v_mfma_f32_16x16x32_bf16 v[66:69], v[186:189], v[218:221], v[66:69]
	v_mfma_f32_16x16x32_bf16 v[66:69], v[168:171], v[214:217], v[66:69]
	v_mfma_f32_16x16x32_bf16 v[82:85], v[168:171], v[206:209], v[82:85]
	v_mfma_f32_16x16x32_bf16 v[82:85], v[186:189], v[210:213], v[82:85]
	v_mfma_f32_16x16x32_bf16 v[86:89], v[164:167], v[210:213], v[86:89]
	v_mfma_f32_16x16x32_bf16 v[86:89], v[160:163], v[206:209], v[86:89]
	v_mfma_f32_16x16x32_bf16 v[102:105], v[160:163], v[198:201], v[102:105]
	v_mfma_f32_16x16x32_bf16 v[102:105], v[164:167], v[202:205], v[102:105]
	v_mfma_f32_16x16x32_bf16 v[98:101], v[186:189], v[202:205], v[98:101]
	v_mfma_f32_16x16x32_bf16 v[98:101], v[168:171], v[198:201], v[98:101]
	v_mfma_f32_16x16x32_bf16 v[114:117], v[168:171], v[190:193], v[114:117]
	v_mfma_f32_16x16x32_bf16 v[114:117], v[186:189], v[194:197], v[114:117]
	v_mfma_f32_16x16x32_bf16 v[118:121], v[164:167], v[194:197], v[118:121]
	v_mfma_f32_16x16x32_bf16 v[118:121], v[160:163], v[190:193], v[118:121]
	s_barrier
	s_add_i32 s30, s62, s49
	s_mov_b32 m0, s30
	ds_read_b128 v[190:193], v184 offset:49152
	ds_read_b128 v[194:197], v184 offset:50176
	ds_read_b128 v[198:201], v184 offset:51200
	ds_read_b128 v[202:205], v184 offset:52224
	ds_read_b128 v[206:209], v184 offset:53248
	ds_read_b128 v[210:213], v184 offset:54272
	ds_read_b128 v[214:217], v184 offset:55296
	ds_read_b128 v[218:221], v184 offset:56320
	global_load_lds_dwordx4 v0, s[64:65]
	s_add_i32 m0, s30, 0x2000
	s_add_i32 s30, s63, s49
	global_load_lds_dwordx4 v142, s[64:65]
	s_mov_b32 m0, s30
	s_nop 0
	global_load_lds_dwordx4 v0, s[66:67]
	s_add_i32 m0, s30, 0x2000
	s_nop 0
	global_load_lds_dwordx4 v142, s[66:67]
	s_mov_b32 m0, s95
	s_nop 0
	global_load_lds_dwordx4 v138, s[68:69]
	s_mov_b32 m0, s54
	s_nop 0
	global_load_lds_dwordx4 v140, s[68:69]
	s_waitcnt vmcnt(8)
	s_waitcnt lgkmcnt(0)
	s_barrier
	s_waitcnt lgkmcnt(0)
	v_mfma_f32_16x16x32_bf16 v[62:65], v[130:133], v[190:193], v[62:65]
	v_mfma_f32_16x16x32_bf16 v[62:65], v[134:137], v[194:197], v[62:65]
	v_mfma_f32_16x16x32_bf16 v[58:61], v[156:159], v[194:197], v[58:61]
	v_mfma_f32_16x16x32_bf16 v[58:61], v[152:155], v[190:193], v[58:61]
	v_mfma_f32_16x16x32_bf16 v[42:45], v[152:155], v[198:201], v[42:45]
	v_mfma_f32_16x16x32_bf16 v[42:45], v[156:159], v[202:205], v[42:45]
	v_mfma_f32_16x16x32_bf16 v[46:49], v[134:137], v[202:205], v[46:49]
	v_mfma_f32_16x16x32_bf16 v[46:49], v[130:133], v[198:201], v[46:49]
	v_mfma_f32_16x16x32_bf16 v[30:33], v[130:133], v[206:209], v[30:33]
	v_mfma_f32_16x16x32_bf16 v[30:33], v[134:137], v[210:213], v[30:33]
	v_mfma_f32_16x16x32_bf16 v[26:29], v[156:159], v[210:213], v[26:29]
	v_mfma_f32_16x16x32_bf16 v[26:29], v[152:155], v[206:209], v[26:29]
	v_mfma_f32_16x16x32_bf16 v[10:13], v[152:155], v[214:217], v[10:13]
	v_mfma_f32_16x16x32_bf16 v[10:13], v[156:159], v[218:221], v[10:13]
	v_mfma_f32_16x16x32_bf16 v[14:17], v[134:137], v[218:221], v[14:17]
	v_mfma_f32_16x16x32_bf16 v[14:17], v[130:133], v[214:217], v[14:17]
	v_mfma_f32_16x16x32_bf16 v[6:9], v[160:163], v[214:217], v[6:9]
	v_mfma_f32_16x16x32_bf16 v[6:9], v[164:167], v[218:221], v[6:9]
	v_mfma_f32_16x16x32_bf16 v[2:5], v[186:189], v[218:221], v[2:5]
	v_mfma_f32_16x16x32_bf16 v[2:5], v[168:171], v[214:217], v[2:5]
	v_mfma_f32_16x16x32_bf16 v[18:21], v[168:171], v[206:209], v[18:21]
	v_mfma_f32_16x16x32_bf16 v[18:21], v[186:189], v[210:213], v[18:21]
	v_mfma_f32_16x16x32_bf16 v[22:25], v[164:167], v[210:213], v[22:25]
	v_mfma_f32_16x16x32_bf16 v[22:25], v[160:163], v[206:209], v[22:25]
	v_mfma_f32_16x16x32_bf16 v[38:41], v[160:163], v[198:201], v[38:41]
	v_mfma_f32_16x16x32_bf16 v[38:41], v[164:167], v[202:205], v[38:41]
	v_mfma_f32_16x16x32_bf16 v[34:37], v[186:189], v[202:205], v[34:37]
	v_mfma_f32_16x16x32_bf16 v[34:37], v[168:171], v[198:201], v[34:37]
	v_mfma_f32_16x16x32_bf16 v[50:53], v[168:171], v[190:193], v[50:53]
	v_mfma_f32_16x16x32_bf16 v[50:53], v[186:189], v[194:197], v[50:53]
	v_mfma_f32_16x16x32_bf16 v[54:57], v[164:167], v[194:197], v[54:57]
	v_mfma_f32_16x16x32_bf16 v[54:57], v[160:163], v[190:193], v[54:57]
	s_barrier
	s_add_u32 s28, s28, 0x100
	s_addc_u32 s29, s29, 0
	s_add_u32 s23, s23, 0x100
	s_addc_u32 s40, s40, 0
	s_cmp_ge_i32 s41, s61
	s_mov_b32 s30, s41
	s_cbranch_scc1 .Lpeel_done_217
.LBB0_217:
	s_add_i32 s41, s30, 2
	s_add_u32 vcc_lo, s28, 0x80
	s_addc_u32 s31, s29, 0
	s_add_i32 s62, 0, 0x10000
	s_cmp_eq_u32 s13, s30
	s_cselect_b32 s31, s25, s31
	s_cselect_b32 s30, s24, vcc_lo
	v_add_u32_e32 v145, s62, v175
	s_cselect_b32 vcc_hi, s27, s40
	s_cselect_b32 vcc_lo, s26, s23
	s_add_i32 s63, 0, 0x14000
	ds_read_b128 v[130:133], v145
	ds_read_b128 v[134:137], v145 offset:1024
	ds_read_b128 v[152:155], v145 offset:2048
	ds_read_b128 v[156:159], v145 offset:3072
	v_add_u32_e32 v145, s63, v175
	ds_read_b128 v[160:163], v145
	ds_read_b128 v[164:167], v145 offset:1024
	ds_read_b128 v[168:171], v145 offset:2048
	ds_read_b128 v[186:189], v145 offset:3072
	s_add_i32 m0, s93, 0xc000
	ds_read_b128 v[190:193], v184
	ds_read_b128 v[194:197], v184 offset:1024
	ds_read_b128 v[198:201], v184 offset:2048
	ds_read_b128 v[202:205], v184 offset:3072
	ds_read_b128 v[206:209], v184 offset:4096
	ds_read_b128 v[210:213], v184 offset:5120
	ds_read_b128 v[214:217], v184 offset:6144
	ds_read_b128 v[218:221], v184 offset:7168
	global_load_lds_dwordx4 v148, s[28:29]
	s_add_i32 m0, s93, 0xe000
	s_nop 0
	global_load_lds_dwordx4 v150, s[28:29]
	s_waitcnt vmcnt(8)
	s_waitcnt lgkmcnt(0)
	s_barrier
	s_waitcnt lgkmcnt(0)
	v_mfma_f32_16x16x32_bf16 v[126:129], v[130:133], v[190:193], v[126:129]
	v_mfma_f32_16x16x32_bf16 v[126:129], v[134:137], v[194:197], v[126:129]
	v_mfma_f32_16x16x32_bf16 v[122:125], v[156:159], v[194:197], v[122:125]
	v_mfma_f32_16x16x32_bf16 v[122:125], v[152:155], v[190:193], v[122:125]
	v_mfma_f32_16x16x32_bf16 v[106:109], v[152:155], v[198:201], v[106:109]
	v_mfma_f32_16x16x32_bf16 v[106:109], v[156:159], v[202:205], v[106:109]
	v_mfma_f32_16x16x32_bf16 v[110:113], v[134:137], v[202:205], v[110:113]
	v_mfma_f32_16x16x32_bf16 v[110:113], v[130:133], v[198:201], v[110:113]
	v_mfma_f32_16x16x32_bf16 v[94:97], v[130:133], v[206:209], v[94:97]
	v_mfma_f32_16x16x32_bf16 v[94:97], v[134:137], v[210:213], v[94:97]
	v_mfma_f32_16x16x32_bf16 v[90:93], v[156:159], v[210:213], v[90:93]
	v_mfma_f32_16x16x32_bf16 v[90:93], v[152:155], v[206:209], v[90:93]
	v_mfma_f32_16x16x32_bf16 v[74:77], v[152:155], v[214:217], v[74:77]
	v_mfma_f32_16x16x32_bf16 v[74:77], v[156:159], v[218:221], v[74:77]
	v_mfma_f32_16x16x32_bf16 v[78:81], v[134:137], v[218:221], v[78:81]
	v_mfma_f32_16x16x32_bf16 v[78:81], v[130:133], v[214:217], v[78:81]
	v_mfma_f32_16x16x32_bf16 v[70:73], v[160:163], v[214:217], v[70:73]
	v_mfma_f32_16x16x32_bf16 v[70:73], v[164:167], v[218:221], v[70:73]
	v_mfma_f32_16x16x32_bf16 v[66:69], v[186:189], v[218:221], v[66:69]
	v_mfma_f32_16x16x32_bf16 v[66:69], v[168:171], v[214:217], v[66:69]
	v_mfma_f32_16x16x32_bf16 v[82:85], v[168:171], v[206:209], v[82:85]
	v_mfma_f32_16x16x32_bf16 v[82:85], v[186:189], v[210:213], v[82:85]
	v_mfma_f32_16x16x32_bf16 v[86:89], v[164:167], v[210:213], v[86:89]
	v_mfma_f32_16x16x32_bf16 v[86:89], v[160:163], v[206:209], v[86:89]
	v_mfma_f32_16x16x32_bf16 v[102:105], v[160:163], v[198:201], v[102:105]
	v_mfma_f32_16x16x32_bf16 v[102:105], v[164:167], v[202:205], v[102:105]
	v_mfma_f32_16x16x32_bf16 v[98:101], v[186:189], v[202:205], v[98:101]
	v_mfma_f32_16x16x32_bf16 v[98:101], v[168:171], v[198:201], v[98:101]
	v_mfma_f32_16x16x32_bf16 v[114:117], v[168:171], v[190:193], v[114:117]
	v_mfma_f32_16x16x32_bf16 v[114:117], v[186:189], v[194:197], v[114:117]
	v_mfma_f32_16x16x32_bf16 v[118:121], v[164:167], v[194:197], v[118:121]
	v_mfma_f32_16x16x32_bf16 v[118:121], v[160:163], v[190:193], v[118:121]
	s_barrier
	s_add_i32 s62, s62, s49
	s_add_u32 s64, vcc_lo, s98
	s_addc_u32 s65, vcc_hi, s99
	s_mov_b32 m0, s62
	ds_read_b128 v[190:193], v184 offset:16384
	ds_read_b128 v[194:197], v184 offset:17408
	ds_read_b128 v[198:201], v184 offset:18432
	ds_read_b128 v[202:205], v184 offset:19456
	ds_read_b128 v[206:209], v184 offset:20480
	ds_read_b128 v[210:213], v184 offset:21504
	ds_read_b128 v[214:217], v184 offset:22528
	ds_read_b128 v[218:221], v184 offset:23552
	global_load_lds_dwordx4 v0, vcc
	s_add_i32 m0, s62, 0x2000
	v_lshl_add_u64 v[222:223], vcc, 0, v[142:143]
	s_add_u32 vcc_lo, vcc_lo, s96
	s_addc_u32 vcc_hi, vcc_hi, 0
	s_add_i32 s62, s63, s49
	global_load_lds_dwordx4 v[222:223], off
	s_add_u32 s66, vcc_lo, s98
	s_addc_u32 s67, vcc_hi, s99
	s_mov_b32 m0, s62
	global_load_lds_dwordx4 v0, vcc
	s_add_i32 m0, s62, 0x2000
	s_add_u32 s68, s30, s98
	s_addc_u32 s69, s31, s99
	global_load_lds_dwordx4 v142, vcc
	s_mov_b32 m0, s93
	global_load_lds_dwordx4 v138, s[30:31]
	s_mov_b32 m0, s88
	s_nop 0
	global_load_lds_dwordx4 v140, s[30:31]
	s_waitcnt vmcnt(8)
	s_waitcnt lgkmcnt(0)
	s_barrier
	s_waitcnt lgkmcnt(0)
	v_mfma_f32_16x16x32_bf16 v[62:65], v[130:133], v[190:193], v[62:65]
	v_mfma_f32_16x16x32_bf16 v[62:65], v[134:137], v[194:197], v[62:65]
	v_mfma_f32_16x16x32_bf16 v[58:61], v[156:159], v[194:197], v[58:61]
	v_mfma_f32_16x16x32_bf16 v[58:61], v[152:155], v[190:193], v[58:61]
	v_mfma_f32_16x16x32_bf16 v[42:45], v[152:155], v[198:201], v[42:45]
	v_mfma_f32_16x16x32_bf16 v[42:45], v[156:159], v[202:205], v[42:45]
	v_mfma_f32_16x16x32_bf16 v[46:49], v[134:137], v[202:205], v[46:49]
	v_mfma_f32_16x16x32_bf16 v[46:49], v[130:133], v[198:201], v[46:49]
	v_mfma_f32_16x16x32_bf16 v[30:33], v[130:133], v[206:209], v[30:33]
	v_mfma_f32_16x16x32_bf16 v[30:33], v[134:137], v[210:213], v[30:33]
	v_mfma_f32_16x16x32_bf16 v[26:29], v[156:159], v[210:213], v[26:29]
	v_mfma_f32_16x16x32_bf16 v[26:29], v[152:155], v[206:209], v[26:29]
	v_mfma_f32_16x16x32_bf16 v[10:13], v[152:155], v[214:217], v[10:13]
	v_mfma_f32_16x16x32_bf16 v[10:13], v[156:159], v[218:221], v[10:13]
	v_mfma_f32_16x16x32_bf16 v[14:17], v[134:137], v[218:221], v[14:17]
	v_mfma_f32_16x16x32_bf16 v[14:17], v[130:133], v[214:217], v[14:17]
	v_mfma_f32_16x16x32_bf16 v[6:9], v[160:163], v[214:217], v[6:9]
	v_mfma_f32_16x16x32_bf16 v[6:9], v[164:167], v[218:221], v[6:9]
	v_mfma_f32_16x16x32_bf16 v[2:5], v[186:189], v[218:221], v[2:5]
	v_mfma_f32_16x16x32_bf16 v[2:5], v[168:171], v[214:217], v[2:5]
	v_mfma_f32_16x16x32_bf16 v[18:21], v[168:171], v[206:209], v[18:21]
	v_mfma_f32_16x16x32_bf16 v[18:21], v[186:189], v[210:213], v[18:21]
	v_mfma_f32_16x16x32_bf16 v[22:25], v[164:167], v[210:213], v[22:25]
	v_mfma_f32_16x16x32_bf16 v[22:25], v[160:163], v[206:209], v[22:25]
	v_mfma_f32_16x16x32_bf16 v[38:41], v[160:163], v[198:201], v[38:41]
	v_mfma_f32_16x16x32_bf16 v[38:41], v[164:167], v[202:205], v[38:41]
	v_mfma_f32_16x16x32_bf16 v[34:37], v[186:189], v[202:205], v[34:37]
	v_mfma_f32_16x16x32_bf16 v[34:37], v[168:171], v[198:201], v[34:37]
	v_mfma_f32_16x16x32_bf16 v[50:53], v[168:171], v[190:193], v[50:53]
	v_mfma_f32_16x16x32_bf16 v[50:53], v[186:189], v[194:197], v[50:53]
	v_mfma_f32_16x16x32_bf16 v[54:57], v[164:167], v[194:197], v[54:57]
	v_mfma_f32_16x16x32_bf16 v[54:57], v[160:163], v[190:193], v[54:57]
	s_barrier
	s_add_i32 s62, 0, 0x18000
	v_add_u32_e32 v145, s62, v175
	s_add_i32 s63, 0, 0x1c000
	ds_read_b128 v[130:133], v145
	ds_read_b128 v[134:137], v145 offset:1024
	ds_read_b128 v[152:155], v145 offset:2048
	ds_read_b128 v[156:159], v145 offset:3072
	v_add_u32_e32 v145, s63, v175
	ds_read_b128 v[160:163], v145
	ds_read_b128 v[164:167], v145 offset:1024
	ds_read_b128 v[168:171], v145 offset:2048
	ds_read_b128 v[186:189], v145 offset:3072
	s_add_u32 s30, s30, s96
	s_addc_u32 s31, s31, 0
	s_mov_b32 m0, s89
	ds_read_b128 v[190:193], v184 offset:32768
	ds_read_b128 v[194:197], v184 offset:33792
	ds_read_b128 v[198:201], v184 offset:34816
	ds_read_b128 v[202:205], v184 offset:35840
	ds_read_b128 v[206:209], v184 offset:36864
	ds_read_b128 v[210:213], v184 offset:37888
	ds_read_b128 v[214:217], v184 offset:38912
	ds_read_b128 v[218:221], v184 offset:39936
	global_load_lds_dwordx4 v138, s[30:31]
	s_mov_b32 m0, s52
	s_nop 0
	global_load_lds_dwordx4 v140, s[30:31]
	s_waitcnt vmcnt(8)
	s_waitcnt lgkmcnt(0)
	s_barrier
	s_waitcnt lgkmcnt(0)
	v_mfma_f32_16x16x32_bf16 v[126:129], v[130:133], v[190:193], v[126:129]
	v_mfma_f32_16x16x32_bf16 v[126:129], v[134:137], v[194:197], v[126:129]
	v_mfma_f32_16x16x32_bf16 v[122:125], v[156:159], v[194:197], v[122:125]
	v_mfma_f32_16x16x32_bf16 v[122:125], v[152:155], v[190:193], v[122:125]
	v_mfma_f32_16x16x32_bf16 v[106:109], v[152:155], v[198:201], v[106:109]
	v_mfma_f32_16x16x32_bf16 v[106:109], v[156:159], v[202:205], v[106:109]
	v_mfma_f32_16x16x32_bf16 v[110:113], v[134:137], v[202:205], v[110:113]
	v_mfma_f32_16x16x32_bf16 v[110:113], v[130:133], v[198:201], v[110:113]
	v_mfma_f32_16x16x32_bf16 v[94:97], v[130:133], v[206:209], v[94:97]
	v_mfma_f32_16x16x32_bf16 v[94:97], v[134:137], v[210:213], v[94:97]
	v_mfma_f32_16x16x32_bf16 v[90:93], v[156:159], v[210:213], v[90:93]
	v_mfma_f32_16x16x32_bf16 v[90:93], v[152:155], v[206:209], v[90:93]
	v_mfma_f32_16x16x32_bf16 v[74:77], v[152:155], v[214:217], v[74:77]
	v_mfma_f32_16x16x32_bf16 v[74:77], v[156:159], v[218:221], v[74:77]
	v_mfma_f32_16x16x32_bf16 v[78:81], v[134:137], v[218:221], v[78:81]
	v_mfma_f32_16x16x32_bf16 v[78:81], v[130:133], v[214:217], v[78:81]
	v_mfma_f32_16x16x32_bf16 v[70:73], v[160:163], v[214:217], v[70:73]
	v_mfma_f32_16x16x32_bf16 v[70:73], v[164:167], v[218:221], v[70:73]
	v_mfma_f32_16x16x32_bf16 v[66:69], v[186:189], v[218:221], v[66:69]
	v_mfma_f32_16x16x32_bf16 v[66:69], v[168:171], v[214:217], v[66:69]
	v_mfma_f32_16x16x32_bf16 v[82:85], v[168:171], v[206:209], v[82:85]
	v_mfma_f32_16x16x32_bf16 v[82:85], v[186:189], v[210:213], v[82:85]
	v_mfma_f32_16x16x32_bf16 v[86:89], v[164:167], v[210:213], v[86:89]
	v_mfma_f32_16x16x32_bf16 v[86:89], v[160:163], v[206:209], v[86:89]
	v_mfma_f32_16x16x32_bf16 v[102:105], v[160:163], v[198:201], v[102:105]
	v_mfma_f32_16x16x32_bf16 v[102:105], v[164:167], v[202:205], v[102:105]
	v_mfma_f32_16x16x32_bf16 v[98:101], v[186:189], v[202:205], v[98:101]
	v_mfma_f32_16x16x32_bf16 v[98:101], v[168:171], v[198:201], v[98:101]
	v_mfma_f32_16x16x32_bf16 v[114:117], v[168:171], v[190:193], v[114:117]
	v_mfma_f32_16x16x32_bf16 v[114:117], v[186:189], v[194:197], v[114:117]
	v_mfma_f32_16x16x32_bf16 v[118:121], v[164:167], v[194:197], v[118:121]
	v_mfma_f32_16x16x32_bf16 v[118:121], v[160:163], v[190:193], v[118:121]
	s_barrier
	s_add_i32 s30, s62, s49
	s_mov_b32 m0, s30
	ds_read_b128 v[190:193], v184 offset:49152
	ds_read_b128 v[194:197], v184 offset:50176
	ds_read_b128 v[198:201], v184 offset:51200
	ds_read_b128 v[202:205], v184 offset:52224
	ds_read_b128 v[206:209], v184 offset:53248
	ds_read_b128 v[210:213], v184 offset:54272
	ds_read_b128 v[214:217], v184 offset:55296
	ds_read_b128 v[218:221], v184 offset:56320
	global_load_lds_dwordx4 v0, s[64:65]
	s_add_i32 m0, s30, 0x2000
	s_add_i32 s30, s63, s49
	global_load_lds_dwordx4 v142, s[64:65]
	s_mov_b32 m0, s30
	s_nop 0
	global_load_lds_dwordx4 v0, s[66:67]
	s_add_i32 m0, s30, 0x2000
	s_nop 0
	global_load_lds_dwordx4 v142, s[66:67]
	s_mov_b32 m0, s95
	s_nop 0
	global_load_lds_dwordx4 v138, s[68:69]
	s_mov_b32 m0, s54
	s_nop 0
	global_load_lds_dwordx4 v140, s[68:69]
	s_waitcnt vmcnt(8)
	s_waitcnt lgkmcnt(0)
	s_barrier
	s_waitcnt lgkmcnt(0)
	v_mfma_f32_16x16x32_bf16 v[62:65], v[130:133], v[190:193], v[62:65]
	v_mfma_f32_16x16x32_bf16 v[62:65], v[134:137], v[194:197], v[62:65]
	v_mfma_f32_16x16x32_bf16 v[58:61], v[156:159], v[194:197], v[58:61]
	v_mfma_f32_16x16x32_bf16 v[58:61], v[152:155], v[190:193], v[58:61]
	v_mfma_f32_16x16x32_bf16 v[42:45], v[152:155], v[198:201], v[42:45]
	v_mfma_f32_16x16x32_bf16 v[42:45], v[156:159], v[202:205], v[42:45]
	v_mfma_f32_16x16x32_bf16 v[46:49], v[134:137], v[202:205], v[46:49]
	v_mfma_f32_16x16x32_bf16 v[46:49], v[130:133], v[198:201], v[46:49]
	v_mfma_f32_16x16x32_bf16 v[30:33], v[130:133], v[206:209], v[30:33]
	v_mfma_f32_16x16x32_bf16 v[30:33], v[134:137], v[210:213], v[30:33]
	v_mfma_f32_16x16x32_bf16 v[26:29], v[156:159], v[210:213], v[26:29]
	v_mfma_f32_16x16x32_bf16 v[26:29], v[152:155], v[206:209], v[26:29]
	v_mfma_f32_16x16x32_bf16 v[10:13], v[152:155], v[214:217], v[10:13]
	v_mfma_f32_16x16x32_bf16 v[10:13], v[156:159], v[218:221], v[10:13]
	v_mfma_f32_16x16x32_bf16 v[14:17], v[134:137], v[218:221], v[14:17]
	v_mfma_f32_16x16x32_bf16 v[14:17], v[130:133], v[214:217], v[14:17]
	v_mfma_f32_16x16x32_bf16 v[6:9], v[160:163], v[214:217], v[6:9]
	v_mfma_f32_16x16x32_bf16 v[6:9], v[164:167], v[218:221], v[6:9]
	v_mfma_f32_16x16x32_bf16 v[2:5], v[186:189], v[218:221], v[2:5]
	v_mfma_f32_16x16x32_bf16 v[2:5], v[168:171], v[214:217], v[2:5]
	v_mfma_f32_16x16x32_bf16 v[18:21], v[168:171], v[206:209], v[18:21]
	v_mfma_f32_16x16x32_bf16 v[18:21], v[186:189], v[210:213], v[18:21]
	v_mfma_f32_16x16x32_bf16 v[22:25], v[164:167], v[210:213], v[22:25]
	v_mfma_f32_16x16x32_bf16 v[22:25], v[160:163], v[206:209], v[22:25]
	v_mfma_f32_16x16x32_bf16 v[38:41], v[160:163], v[198:201], v[38:41]
	v_mfma_f32_16x16x32_bf16 v[38:41], v[164:167], v[202:205], v[38:41]
	v_mfma_f32_16x16x32_bf16 v[34:37], v[186:189], v[202:205], v[34:37]
	v_mfma_f32_16x16x32_bf16 v[34:37], v[168:171], v[198:201], v[34:37]
	v_mfma_f32_16x16x32_bf16 v[50:53], v[168:171], v[190:193], v[50:53]
	v_mfma_f32_16x16x32_bf16 v[50:53], v[186:189], v[194:197], v[50:53]
	v_mfma_f32_16x16x32_bf16 v[54:57], v[164:167], v[194:197], v[54:57]
	v_mfma_f32_16x16x32_bf16 v[54:57], v[160:163], v[190:193], v[54:57]
	s_barrier
	s_add_u32 s28, s28, 0x100
	s_addc_u32 s29, s29, 0
	s_add_u32 s23, s23, 0x100
	s_addc_u32 s40, s40, 0
	s_cmp_ge_i32 s41, s61
	s_mov_b32 s30, s41
	s_cbranch_scc0 .LBB0_217
